# P0 H rows stored write-through (less dirty L2 at the first grid barrier) + barrier census words pre-filled for the relabelled 256-workgroup grid
# speedup vs baseline: 1.0061x; 1.0061x over previous
; #define LAS __attribute__((address_space(3)))
; __device__ __forceinline__ void xcd_barrier(const XcdBarrier& b) {
;     ...
;     if (threadIdx.x == 0) {
;         unsigned* bar = b.bar;
;         __builtin_amdgcn_s_waitcnt(0);
;         unsigned nloc = b.st[0], nx = b.st[1];
;         if (nloc == 0u) { xcd_barrier_complete(bar, b.x, nloc, nx); b.st[0] = nloc; b.st[1] = nx; }
; __global__ void __launch_bounds__(NWAVES * 64, 2) hybrid_fwd(Args args) {
;     ...
;     volatile LAS unsigned* MISC = (volatile LAS unsigned*)((LAS unsigned char*)lds + LDS_BYTES - 64);
;     if (tid < 16) MISC[tid] = 0u;
;     __syncthreads();
;     XcdBarrier bar = xcd_barrier_post((unsigned*)(ws + WS_BAR), MISC);
.Lgb_post_ok:
	s_mov_b64 exec, s[96:97]
	s_cbranch_execz .Lgb_post_skip
	v_mov_b32_e32 v254, 0x20fc0
	v_mov_b32_e32 v255, 32
	v_mov_b32_e32 v253, 8
	ds_write_b32 v254, v255
	ds_write_b32 v254, v253 offset:4
	s_waitcnt lgkmcnt(0)

; __global__ void __launch_bounds__(NWAVES * 64, 2) hybrid_fwd(Args args) {
;     ...
;         for (int m0 = gw * 4; m0 < M; m0 += NGW * 4) {
;             f32x4 v[4][8]; float s[4] = {0.f, 0.f, 0.f, 0.f};
; #pragma unroll
;             for (int q = 0; q < 4; ++q) { const f32x4* xr = (const f32x4*)(x + (size_t)(m0 + q) * DM) + lane;
; #pragma unroll
;                 for (int j = 0; j < 8; ++j) v[q][j] = xr[64 * j]; }
; #pragma unroll
;             for (int q = 0; q < 4; ++q)
; #pragma unroll
;                 for (int j = 0; j < 8; ++j) s[q] += (v[q][j].x * v[q][j].x + v[q][j].y * v[q][j].y) + (v[q][j].z * v[q][j].z + v[q][j].w * v[q][j].w);
.LBB0_25:
	v_add_co_u32_e32 v48, vcc, 0x1000, v162
	s_mov_b64 s[0:1], vcc
	v_add_co_u32_e32 v166, vcc, s9, v160
	global_load_dwordx4 v[44:47], v[162:163], off nt
	global_load_dwordx4 v[40:43], v[162:163], off offset:1024 nt
	global_load_dwordx4 v[36:39], v[162:163], off offset:2048 nt
	global_load_dwordx4 v[32:35], v[162:163], off offset:3072 nt
	v_addc_co_u32_e32 v167, vcc, 0, v161, vcc
	v_add_co_u32_e32 v168, vcc, s18, v160
	s_add_i32 s8, s8, s12
	s_nop 0
	v_addc_co_u32_e32 v169, vcc, 0, v161, vcc
	v_add_co_u32_e32 v164, vcc, s13, v160
	s_cmpk_lt_i32 s8, 0x4000
	s_nop 0
	v_addc_co_u32_e32 v165, vcc, 0, v161, vcc
	v_add_co_u32_e32 v50, vcc, 0x2000, v162
	s_mov_b64 s[4:5], vcc
	v_addc_co_u32_e64 v49, vcc, 0, v163, s[0:1]
	global_load_dwordx4 v[156:159], v[48:49], off nt
	global_load_dwordx4 v[152:155], v[48:49], off offset:1024 nt
	global_load_dwordx4 v[148:151], v[48:49], off offset:2048 nt
	global_load_dwordx4 v[144:147], v[48:49], off offset:3072 nt
	v_add_co_u32_e32 v48, vcc, 0x3000, v162
	s_mov_b64 s[0:1], vcc
	v_addc_co_u32_e64 v51, vcc, 0, v163, s[4:5]
	v_add_co_u32_e32 v52, vcc, 0x4000, v162
	s_mov_b64 s[4:5], vcc
	global_load_dwordx4 v[140:143], v[50:51], off nt
	global_load_dwordx4 v[136:139], v[50:51], off offset:1024 nt
	global_load_dwordx4 v[132:135], v[50:51], off offset:2048 nt
	global_load_dwordx4 v[124:127], v[50:51], off offset:3072 nt
	v_addc_co_u32_e64 v49, vcc, 0, v163, s[0:1]
	v_add_co_u32_e32 v50, vcc, 0x5000, v162
	s_mov_b64 s[0:1], vcc
	v_addc_co_u32_e64 v53, vcc, 0, v163, s[4:5]
	global_load_dwordx4 v[128:131], v[48:49], off nt
	global_load_dwordx4 v[120:123], v[48:49], off offset:1024 nt
	global_load_dwordx4 v[116:119], v[48:49], off offset:2048 nt
	global_load_dwordx4 v[112:115], v[48:49], off offset:3072 nt
	global_load_dwordx4 v[108:111], v[52:53], off nt
	global_load_dwordx4 v[104:107], v[52:53], off offset:1024 nt
	global_load_dwordx4 v[100:103], v[52:53], off offset:2048 nt
	global_load_dwordx4 v[96:99], v[52:53], off offset:3072 nt
	v_add_co_u32_e32 v48, vcc, 0x6000, v162
	v_addc_co_u32_e64 v51, s[0:1], 0, v163, s[0:1]
	s_nop 0
	v_addc_co_u32_e32 v49, vcc, 0, v163, vcc
	global_load_dwordx4 v[92:95], v[50:51], off nt
	global_load_dwordx4 v[88:91], v[50:51], off offset:1024 nt
	global_load_dwordx4 v[84:87], v[50:51], off offset:2048 nt
	global_load_dwordx4 v[80:83], v[50:51], off offset:3072 nt
	global_load_dwordx4 v[76:79], v[48:49], off nt
	global_load_dwordx4 v[72:75], v[48:49], off offset:1024 nt
	global_load_dwordx4 v[68:71], v[48:49], off offset:2048 nt
	global_load_dwordx4 v[60:63], v[48:49], off offset:3072 nt
	v_add_co_u32_e32 v50, vcc, 0x7000, v162
	s_waitcnt vmcnt(27)
	v_mul_f32_e32 v177, v45, v45
	v_addc_co_u32_e32 v51, vcc, 0, v163, vcc
	global_load_dwordx4 v[64:67], v[50:51], off nt
	global_load_dwordx4 v[56:59], v[50:51], off offset:1024 nt
	global_load_dwordx4 v[52:55], v[50:51], off offset:2048 nt
	s_nop 0
	global_load_dwordx4 v[48:51], v[50:51], off offset:3072 nt
	v_mul_f32_e32 v178, v47, v47
	s_waitcnt vmcnt(30)
	v_mul_f32_e32 v179, v41, v41
	v_mul_f32_e32 v180, v43, v43
	s_waitcnt vmcnt(29)
	v_mul_f32_e32 v181, v37, v37
	v_mul_f32_e32 v182, v39, v39
	v_fmac_f32_e32 v177, v44, v44
	v_fmac_f32_e32 v178, v46, v46
	v_fmac_f32_e32 v179, v40, v40
	v_fmac_f32_e32 v180, v42, v42
	s_waitcnt vmcnt(28)
	v_mul_f32_e32 v183, v33, v33
	v_mul_f32_e32 v186, v35, v35
	v_fmac_f32_e32 v181, v36, v36
	v_fmac_f32_e32 v182, v38, v38
	v_add_f32_e32 v177, v177, v178
	v_add_f32_e32 v178, v179, v180
	v_fmac_f32_e32 v183, v32, v32
	v_fmac_f32_e32 v186, v34, v34
	v_add_f32_e32 v179, v181, v182
	s_waitcnt vmcnt(27)
	v_mul_f32_e32 v181, v157, v157
	v_mul_f32_e32 v182, v159, v159
	v_add_f32_e32 v177, v177, v178
	v_add_f32_e32 v180, v183, v186
	s_waitcnt vmcnt(26)
	v_mul_f32_e32 v183, v153, v153
	s_waitcnt vmcnt(23)
	v_mul_f32_e32 v178, v141, v141
	v_mul_f32_e32 v191, v143, v143
	s_waitcnt vmcnt(22)
	v_mul_f32_e32 v192, v137, v137
	v_mul_f32_e32 v193, v139, v139
	s_waitcnt vmcnt(21)
	v_mul_f32_e32 v194, v133, v133
	v_mul_f32_e32 v195, v135, v135
	s_waitcnt vmcnt(20)
	v_mul_f32_e32 v196, v125, v125
	v_mul_f32_e32 v197, v127, v127
	v_mul_f32_e32 v186, v155, v155
	v_mul_f32_e32 v187, v149, v149
	v_mul_f32_e32 v188, v151, v151
	v_fmac_f32_e32 v181, v156, v156
	v_fmac_f32_e32 v182, v158, v158
	v_add_f32_e32 v177, v177, v179
	v_fmac_f32_e32 v178, v140, v140
	v_fmac_f32_e32 v191, v142, v142
	v_fmac_f32_e32 v192, v136, v136
	v_fmac_f32_e32 v193, v138, v138
	v_fmac_f32_e32 v194, v132, v132
	v_fmac_f32_e32 v195, v134, v134
	v_fmac_f32_e32 v196, v124, v124
	v_fmac_f32_e32 v197, v126, v126
	v_mul_f32_e32 v189, v145, v145
	v_mul_f32_e32 v190, v147, v147
	v_fmac_f32_e32 v183, v152, v152
	v_fmac_f32_e32 v186, v154, v154
	v_fmac_f32_e32 v187, v148, v148
	v_fmac_f32_e32 v188, v150, v150
	v_add_f32_e32 v179, v181, v182
	v_add_f32_e32 v177, v177, v180
	v_add_f32_e32 v178, v178, v191
	v_add_f32_e32 v180, v192, v193
	v_add_f32_e32 v191, v194, v195
	v_add_f32_e32 v192, v196, v197
	s_waitcnt vmcnt(15)
	v_mul_f32_e32 v193, v109, v109
	v_mul_f32_e32 v194, v111, v111
	s_waitcnt vmcnt(14)
	v_mul_f32_e32 v195, v105, v105
	v_mul_f32_e32 v196, v107, v107
	s_waitcnt vmcnt(13)
	v_mul_f32_e32 v197, v101, v101
	v_mul_f32_e32 v201, v103, v103
	v_fmac_f32_e32 v189, v144, v144
	v_fmac_f32_e32 v190, v146, v146
	v_add_f32_e32 v181, v183, v186
	v_add_f32_e32 v182, v187, v188
	v_mul_f32_e32 v186, v129, v129
	v_mul_f32_e32 v187, v131, v131
	s_waitcnt vmcnt(12)
; __device__ __forceinline__ float wave_sum(float v) {
; #pragma unroll
;     for (int o = 1; o < 64; o <<= 1) v += __shfl_xor(v, o);
;     return v;
; __global__ void __launch_bounds__(NWAVES * 64, 2) hybrid_fwd(Args args) {
;     ...
;             for (int q = 0; q < 4; ++q)
; #pragma unroll
;                 for (int j = 0; j < 8; ++j) s[q] += (v[q][j].x * v[q][j].x + v[q][j].y * v[q][j].y) + (v[q][j].z * v[q][j].z + v[q][j].w * v[q][j].w);
; #pragma unroll
;             for (int q = 0; q < 4; ++q) { const float rs = __builtin_amdgcn_rsqf(wave_sum(s[q]) * (1.f / DM) + NORM_EPS);
	v_mul_f32_e32 v202, v97, v97
	v_mul_f32_e32 v203, v99, v99
	v_add_f32_e32 v177, v177, v179
	v_add_f32_e32 v178, v178, v180
	v_fmac_f32_e32 v193, v108, v108
	v_fmac_f32_e32 v194, v110, v110
	v_fmac_f32_e32 v195, v104, v104
	v_fmac_f32_e32 v196, v106, v106
	v_fmac_f32_e32 v197, v100, v100
	v_fmac_f32_e32 v201, v102, v102
	v_add_f32_e32 v183, v189, v190
	v_mul_f32_e32 v188, v121, v121
	v_mul_f32_e32 v189, v123, v123
	v_mul_f32_e32 v190, v117, v117
	v_mul_f32_e32 v198, v119, v119
	v_mul_f32_e32 v199, v113, v113
	v_mul_f32_e32 v200, v115, v115
	v_fmac_f32_e32 v186, v128, v128
	v_fmac_f32_e32 v187, v130, v130
	v_fmac_f32_e32 v202, v96, v96
	v_fmac_f32_e32 v203, v98, v98
	v_add_f32_e32 v177, v177, v181
	v_add_f32_e32 v178, v178, v191
	v_add_f32_e32 v181, v193, v194
	v_add_f32_e32 v191, v195, v196
	v_add_f32_e32 v193, v197, v201
	s_waitcnt vmcnt(7)
	v_mul_f32_e32 v195, v77, v77
	v_mul_f32_e32 v196, v79, v79
	s_waitcnt vmcnt(6)
	v_mul_f32_e32 v197, v73, v73
	v_mul_f32_e32 v201, v75, v75
	v_fmac_f32_e32 v188, v120, v120
	v_fmac_f32_e32 v189, v122, v122
	v_fmac_f32_e32 v190, v116, v116
	v_fmac_f32_e32 v198, v118, v118
	v_fmac_f32_e32 v199, v112, v112
	v_fmac_f32_e32 v200, v114, v114
	v_add_f32_e32 v179, v186, v187
	v_add_f32_e32 v194, v202, v203
	s_waitcnt vmcnt(5)
	v_mul_f32_e32 v202, v69, v69
	v_mul_f32_e32 v203, v71, v71
	v_add_f32_e32 v177, v177, v182
	v_add_f32_e32 v178, v178, v192
	v_add_f32_e32 v181, v181, v191
	v_fmac_f32_e32 v195, v76, v76
	v_fmac_f32_e32 v196, v78, v78
	v_fmac_f32_e32 v197, v72, v72
	v_fmac_f32_e32 v201, v74, v74
	v_add_f32_e32 v180, v188, v189
	v_add_f32_e32 v186, v190, v198
	v_add_f32_e32 v187, v199, v200
	v_mul_f32_e32 v188, v93, v93
	v_mul_f32_e32 v189, v95, v95
	v_mul_f32_e32 v190, v89, v89
	v_mul_f32_e32 v198, v91, v91
	v_mul_f32_e32 v199, v85, v85
	v_mul_f32_e32 v200, v87, v87
	s_waitcnt vmcnt(4)
	v_mul_f32_e32 v206, v61, v61
	v_mul_f32_e32 v207, v63, v63
	v_fmac_f32_e32 v202, v68, v68
	v_fmac_f32_e32 v203, v70, v70
	v_add_f32_e32 v177, v177, v183
	v_add_f32_e32 v178, v178, v179
	v_add_f32_e32 v179, v181, v193
	v_add_f32_e32 v181, v195, v196
	v_add_f32_e32 v183, v197, v201
	v_mul_f32_e32 v204, v81, v81
	v_mul_f32_e32 v205, v83, v83
	v_fmac_f32_e32 v188, v92, v92
	v_fmac_f32_e32 v189, v94, v94
	v_fmac_f32_e32 v190, v88, v88
	v_fmac_f32_e32 v198, v90, v90
	v_fmac_f32_e32 v199, v84, v84
	v_fmac_f32_e32 v200, v86, v86
	v_fmac_f32_e32 v206, v60, v60
	v_fmac_f32_e32 v207, v62, v62
	s_waitcnt vmcnt(3)
	v_mul_f32_e32 v191, v65, v65
	v_mul_f32_e32 v192, v67, v67
	v_add_f32_e32 v193, v202, v203
	ds_bpermute_b32 v196, v170, v177
	v_add_f32_e32 v178, v178, v180
	v_add_f32_e32 v180, v181, v183
	v_fmac_f32_e32 v204, v80, v80
	v_fmac_f32_e32 v205, v82, v82
	v_add_f32_e32 v182, v188, v189
	v_add_f32_e32 v188, v190, v198
	v_add_f32_e32 v189, v199, v200
	s_waitcnt vmcnt(2)
	v_mul_f32_e32 v198, v57, v57
	v_mul_f32_e32 v199, v59, v59
	v_add_f32_e32 v195, v206, v207
	v_fmac_f32_e32 v191, v64, v64
	v_fmac_f32_e32 v192, v66, v66
	v_add_f32_e32 v179, v179, v194
	v_add_f32_e32 v180, v180, v193
	v_add_f32_e32 v190, v204, v205
	s_waitcnt vmcnt(1)
	v_mul_f32_e32 v200, v53, v53
	v_mul_f32_e32 v204, v55, v55
	v_fmac_f32_e32 v198, v56, v56
	v_fmac_f32_e32 v199, v58, v58
	v_add_f32_e32 v181, v191, v192
	v_add_f32_e32 v179, v179, v182
	v_add_f32_e32 v180, v180, v195
	s_waitcnt vmcnt(0)
	v_mul_f32_e32 v205, v49, v49
	v_mul_f32_e32 v208, v51, v51
	v_fmac_f32_e32 v200, v52, v52
	v_fmac_f32_e32 v204, v54, v54
	v_add_f32_e32 v183, v198, v199
	v_add_f32_e32 v179, v179, v188
	v_add_f32_e32 v180, v180, v181
	v_fmac_f32_e32 v205, v48, v48
	v_fmac_f32_e32 v208, v50, v50
	v_add_f32_e32 v191, v200, v204
	v_add_f32_e32 v179, v179, v189
	v_add_f32_e32 v180, v180, v183
	v_add_f32_e32 v192, v205, v208
	v_add_f32_e32 v179, v179, v190
	s_waitcnt lgkmcnt(0)
	v_add_f32_e32 v177, v177, v196
	v_add_f32_e32 v180, v180, v191
	v_add_f32_e32 v178, v178, v186
	ds_bpermute_b32 v181, v170, v179
	ds_bpermute_b32 v183, v171, v177
	v_add_f32_e32 v180, v180, v192
	v_add_f32_e32 v178, v178, v187
	ds_bpermute_b32 v186, v170, v180
	ds_bpermute_b32 v182, v170, v178
	s_waitcnt lgkmcnt(3)
	v_add_f32_e32 v179, v179, v181
	s_waitcnt lgkmcnt(2)
	v_add_f32_e32 v177, v177, v183
	ds_bpermute_b32 v181, v171, v179
	ds_bpermute_b32 v183, v172, v177
	s_waitcnt lgkmcnt(3)
	v_add_f32_e32 v180, v180, v186
	s_waitcnt lgkmcnt(2)
	v_add_f32_e32 v178, v178, v182
	ds_bpermute_b32 v186, v171, v180
	ds_bpermute_b32 v182, v171, v178
	s_waitcnt lgkmcnt(3)
	v_add_f32_e32 v179, v179, v181
	s_waitcnt lgkmcnt(2)
	v_add_f32_e32 v177, v177, v183
	ds_bpermute_b32 v181, v172, v179
	ds_bpermute_b32 v183, v173, v177
	s_waitcnt lgkmcnt(3)
	v_add_f32_e32 v180, v180, v186
	s_waitcnt lgkmcnt(2)
	v_add_f32_e32 v178, v178, v182
	ds_bpermute_b32 v186, v172, v180
	ds_bpermute_b32 v182, v172, v178
	s_waitcnt lgkmcnt(3)
	v_add_f32_e32 v179, v179, v181
	s_waitcnt lgkmcnt(2)
	v_add_f32_e32 v177, v177, v183
	ds_bpermute_b32 v181, v173, v179
	ds_bpermute_b32 v183, v174, v177
	s_waitcnt lgkmcnt(3)
	v_add_f32_e32 v180, v180, v186
	s_waitcnt lgkmcnt(2)
	v_add_f32_e32 v178, v178, v182
	ds_bpermute_b32 v186, v173, v180
	ds_bpermute_b32 v182, v173, v178
	s_waitcnt lgkmcnt(3)
	v_add_f32_e32 v179, v179, v181
	s_waitcnt lgkmcnt(2)
	v_add_f32_e32 v177, v177, v183
	ds_bpermute_b32 v181, v174, v179
	ds_bpermute_b32 v183, v175, v177
	s_waitcnt lgkmcnt(3)
	v_add_f32_e32 v180, v180, v186
	s_waitcnt lgkmcnt(2)
	v_add_f32_e32 v178, v178, v182
	ds_bpermute_b32 v186, v174, v180
	ds_bpermute_b32 v182, v174, v178
	s_waitcnt lgkmcnt(3)
	v_add_f32_e32 v179, v179, v181
	s_waitcnt lgkmcnt(2)
; __device__ __forceinline__ unsigned cvtpk2(float lo, float hi) { unsigned r; asm volatile("v_cvt_pk_bf16_f32 %0, %1, %2" : "=v"(r) : "v"(lo), "v"(hi)); return r; }
; __global__ void __launch_bounds__(NWAVES * 64, 2) hybrid_fwd(Args args) {
;     ...
;             for (int q = 0; q < 4; ++q) { const float rs = __builtin_amdgcn_rsqf(wave_sum(s[q]) * (1.f / DM) + NORM_EPS);
;                 v2u* o8 = (v2u*)(HB + (size_t)(m0 + q) * DM) + lane;
; #pragma unroll
;                 for (int j = 0; j < 8; ++j) { const f32x4 w = wmix[j]; v2u o; o.x = cvtpk2(v[q][j].x * rs * w.x, v[q][j].y * rs * w.y); o.y = cvtpk2(v[q][j].z * rs * w.z, v[q][j].w * rs * w.w); o8[64 * j] = o; } }
	v_add_f32_e32 v177, v177, v183
	ds_bpermute_b32 v181, v175, v179
	v_fmamk_f32 v177, v177, 0x3a000000, v176
	s_waitcnt lgkmcnt(2)
	v_add_f32_e32 v180, v180, v186
	s_waitcnt lgkmcnt(1)
	v_add_f32_e32 v178, v178, v182
	v_rsq_f32_e32 v177, v177
	ds_bpermute_b32 v183, v175, v180
	ds_bpermute_b32 v182, v175, v178
	s_waitcnt lgkmcnt(2)
	v_add_f32_e32 v179, v179, v181
	v_mul_f32_e32 v44, v177, v44
	v_mul_f32_e32 v45, v177, v45
	v_mul_f32_e32 v46, v177, v46
	v_mul_f32_e32 v47, v177, v47
	v_mul_f32_e32 v32, v177, v32
	v_mul_f32_e32 v33, v177, v33
	v_mul_f32_e32 v40, v177, v40
	v_mul_f32_e32 v41, v177, v41
	v_mul_f32_e32 v42, v177, v42
	v_mul_f32_e32 v43, v177, v43
	v_mul_f32_e32 v36, v177, v36
	v_mul_f32_e32 v37, v177, v37
	v_mul_f32_e32 v38, v177, v38
	v_mul_f32_e32 v39, v177, v39
	v_mul_f32_e32 v34, v177, v34
	v_mul_f32_e32 v35, v177, v35
	v_mul_f32_e32 v156, v177, v156
	v_mul_f32_e32 v157, v177, v157
	v_mul_f32_e32 v158, v177, v158
	v_mul_f32_e32 v159, v177, v159
	v_mul_f32_e32 v152, v177, v152
	v_mul_f32_e32 v153, v177, v153
	v_mul_f32_e32 v154, v177, v154
	v_mul_f32_e32 v155, v177, v155
	v_mul_f32_e32 v148, v177, v148
	v_mul_f32_e32 v149, v177, v149
	v_mul_f32_e32 v150, v177, v150
	v_mul_f32_e32 v151, v177, v151
	v_mul_f32_e32 v144, v177, v144
	v_mul_f32_e32 v145, v177, v145
	v_mul_f32_e32 v146, v177, v146
	v_mul_f32_e32 v147, v177, v147
	v_fmamk_f32 v177, v179, 0x3a000000, v176
	s_waitcnt lgkmcnt(1)
	v_add_f32_e32 v179, v180, v183
	v_mul_f32_e32 v44, v28, v44
	v_mul_f32_e32 v45, v29, v45
	v_mul_f32_e32 v46, v30, v46
	v_mul_f32_e32 v47, v31, v47
	v_mul_f32_e32 v180, v16, v32
	v_mul_f32_e32 v181, v17, v33
	v_cvt_pk_bf16_f32 v32, v44, v45
	v_cvt_pk_bf16_f32 v33, v46, v47
	s_waitcnt lgkmcnt(0)
	v_add_f32_e32 v178, v178, v182
	v_mul_f32_e32 v40, v24, v40
	v_mul_f32_e32 v41, v25, v41
	v_mul_f32_e32 v42, v26, v42
	v_mul_f32_e32 v43, v27, v43
	global_store_dwordx2 v[160:161], v[32:33], off sc1
	v_cvt_pk_bf16_f32 v32, v40, v41
	v_cvt_pk_bf16_f32 v33, v42, v43
	v_fmamk_f32 v178, v178, 0x3a000000, v176
	v_mul_f32_e32 v36, v20, v36
	v_mul_f32_e32 v37, v21, v37
	v_mul_f32_e32 v38, v22, v38
	v_mul_f32_e32 v39, v23, v39
	global_store_dwordx2 v[160:161], v[32:33], off offset:512 sc1
	v_cvt_pk_bf16_f32 v32, v36, v37
	v_cvt_pk_bf16_f32 v33, v38, v39
	v_rsq_f32_e32 v178, v178
	v_mul_f32_e32 v34, v18, v34
	v_mul_f32_e32 v35, v19, v35
	global_store_dwordx2 v[160:161], v[32:33], off offset:1024 sc1
	v_cvt_pk_bf16_f32 v32, v180, v181
	v_cvt_pk_bf16_f32 v33, v34, v35
	v_mul_f32_e32 v156, v12, v156
	v_mul_f32_e32 v157, v13, v157
	v_mul_f32_e32 v158, v14, v158
	v_mul_f32_e32 v159, v15, v159
	global_store_dwordx2 v[160:161], v[32:33], off offset:1536 sc1
	v_cvt_pk_bf16_f32 v32, v156, v157
	v_cvt_pk_bf16_f32 v33, v158, v159
	v_mul_f32_e32 v152, v8, v152
	v_mul_f32_e32 v153, v9, v153
	v_mul_f32_e32 v154, v10, v154
	v_mul_f32_e32 v155, v11, v155
	global_store_dwordx2 v[160:161], v[32:33], off offset:2048 sc1
	v_cvt_pk_bf16_f32 v32, v152, v153
	v_cvt_pk_bf16_f32 v33, v154, v155
	v_mul_f32_e32 v148, v4, v148
	v_mul_f32_e32 v149, v5, v149
	v_mul_f32_e32 v150, v6, v150
	v_mul_f32_e32 v151, v7, v151
	global_store_dwordx2 v[160:161], v[32:33], off offset:2560 sc1
	v_cvt_pk_bf16_f32 v32, v148, v149
	v_cvt_pk_bf16_f32 v33, v150, v151
	v_mul_f32_e32 v144, v0, v144
	v_mul_f32_e32 v145, v1, v145
	v_mul_f32_e32 v146, v2, v146
	v_mul_f32_e32 v147, v3, v147
	v_mul_f32_e32 v44, v178, v140
	v_mul_f32_e32 v45, v178, v141
	v_mul_f32_e32 v46, v178, v142
	v_mul_f32_e32 v47, v178, v143
	global_store_dwordx2 v[160:161], v[32:33], off offset:3072 sc1
	v_cvt_pk_bf16_f32 v32, v144, v145
	v_cvt_pk_bf16_f32 v33, v146, v147
	v_mul_f32_e32 v136, v178, v136
	v_mul_f32_e32 v137, v178, v137
	v_mul_f32_e32 v138, v178, v138
	v_mul_f32_e32 v139, v178, v139
	v_mul_f32_e32 v36, v28, v44
	v_mul_f32_e32 v37, v29, v45
	v_mul_f32_e32 v38, v30, v46
	v_mul_f32_e32 v39, v31, v47
	global_store_dwordx2 v[160:161], v[32:33], off offset:3584 sc1
	v_cvt_pk_bf16_f32 v32, v36, v37
	v_cvt_pk_bf16_f32 v33, v38, v39
	v_mul_f32_e32 v132, v178, v132
	v_mul_f32_e32 v133, v178, v133
	v_mul_f32_e32 v134, v178, v134
	v_mul_f32_e32 v135, v178, v135
	v_mul_f32_e32 v40, v24, v136
	v_mul_f32_e32 v41, v25, v137
	v_mul_f32_e32 v42, v26, v138
	v_mul_f32_e32 v43, v27, v139
	global_store_dwordx2 v[166:167], v[32:33], off offset:-4096 sc1
	v_cvt_pk_bf16_f32 v32, v40, v41
	v_cvt_pk_bf16_f32 v33, v42, v43
	v_mul_f32_e32 v124, v178, v124
	v_mul_f32_e32 v125, v178, v125
	v_mul_f32_e32 v126, v178, v126
	v_mul_f32_e32 v127, v178, v127
	v_mul_f32_e32 v44, v20, v132
	v_mul_f32_e32 v45, v21, v133
	v_mul_f32_e32 v46, v22, v134
	v_mul_f32_e32 v47, v23, v135
	global_store_dwordx2 v[168:169], v[32:33], off offset:512 sc1
	v_cvt_pk_bf16_f32 v32, v44, v45
	v_cvt_pk_bf16_f32 v33, v46, v47
	v_rsq_f32_e32 v177, v177
	v_mul_f32_e32 v128, v178, v128
	v_mul_f32_e32 v129, v178, v129
	v_mul_f32_e32 v130, v178, v130
	v_mul_f32_e32 v131, v178, v131
	v_mul_f32_e32 v124, v16, v124
	v_mul_f32_e32 v125, v17, v125
	v_mul_f32_e32 v126, v18, v126
	v_mul_f32_e32 v127, v19, v127
	global_store_dwordx2 v[168:169], v[32:33], off offset:1024 sc1
	v_cvt_pk_bf16_f32 v32, v124, v125
	v_cvt_pk_bf16_f32 v33, v126, v127
	v_mul_f32_e32 v120, v178, v120
	v_mul_f32_e32 v121, v178, v121
	v_mul_f32_e32 v122, v178, v122
	v_mul_f32_e32 v123, v178, v123
	v_mul_f32_e32 v128, v12, v128
	v_mul_f32_e32 v129, v13, v129
	v_mul_f32_e32 v130, v14, v130
	v_mul_f32_e32 v131, v15, v131
	global_store_dwordx2 v[168:169], v[32:33], off offset:1536 sc1
	v_cvt_pk_bf16_f32 v32, v128, v129
	v_cvt_pk_bf16_f32 v33, v130, v131
	v_mul_f32_e32 v116, v178, v116
	v_mul_f32_e32 v117, v178, v117
	v_mul_f32_e32 v118, v178, v118
; __device__ __forceinline__ unsigned cvtpk2(float lo, float hi) { unsigned r; asm volatile("v_cvt_pk_bf16_f32 %0, %1, %2" : "=v"(r) : "v"(lo), "v"(hi)); return r; }
; __global__ void __launch_bounds__(NWAVES * 64, 2) hybrid_fwd(Args args) {
;     ...
;             for (int q = 0; q < 4; ++q) { const float rs = __builtin_amdgcn_rsqf(wave_sum(s[q]) * (1.f / DM) + NORM_EPS);
;                 v2u* o8 = (v2u*)(HB + (size_t)(m0 + q) * DM) + lane;
; #pragma unroll
;                 for (int j = 0; j < 8; ++j) { const f32x4 w = wmix[j]; v2u o; o.x = cvtpk2(v[q][j].x * rs * w.x, v[q][j].y * rs * w.y); o.y = cvtpk2(v[q][j].z * rs * w.z, v[q][j].w * rs * w.w); o8[64 * j] = o; } }
	v_mul_f32_e32 v119, v178, v119
	v_mul_f32_e32 v120, v8, v120
	v_mul_f32_e32 v121, v9, v121
	v_mul_f32_e32 v122, v10, v122
	v_mul_f32_e32 v123, v11, v123
	global_store_dwordx2 v[168:169], v[32:33], off offset:2048 sc1
	v_cvt_pk_bf16_f32 v32, v120, v121
	v_cvt_pk_bf16_f32 v33, v122, v123
	v_mul_f32_e32 v112, v178, v112
	v_mul_f32_e32 v113, v178, v113
	v_mul_f32_e32 v114, v178, v114
	v_mul_f32_e32 v115, v178, v115
	v_mul_f32_e32 v116, v4, v116
	v_mul_f32_e32 v117, v5, v117
	v_mul_f32_e32 v118, v6, v118
	v_mul_f32_e32 v119, v7, v119
	global_store_dwordx2 v[168:169], v[32:33], off offset:2560 sc1
	v_cvt_pk_bf16_f32 v32, v116, v117
	v_cvt_pk_bf16_f32 v33, v118, v119
	v_mul_f32_e32 v112, v0, v112
	v_mul_f32_e32 v113, v1, v113
	v_mul_f32_e32 v114, v2, v114
	v_mul_f32_e32 v115, v3, v115
	v_mul_f32_e32 v108, v177, v108
	v_mul_f32_e32 v109, v177, v109
	v_mul_f32_e32 v110, v177, v110
	v_mul_f32_e32 v111, v177, v111
	global_store_dwordx2 v[168:169], v[32:33], off offset:3072 sc1
	v_cvt_pk_bf16_f32 v32, v112, v113
	v_cvt_pk_bf16_f32 v33, v114, v115
	v_mul_f32_e32 v104, v177, v104
	v_mul_f32_e32 v105, v177, v105
	v_mul_f32_e32 v106, v177, v106
	v_mul_f32_e32 v107, v177, v107
	v_mul_f32_e32 v34, v28, v108
	v_mul_f32_e32 v35, v29, v109
	v_mul_f32_e32 v108, v30, v110
	v_mul_f32_e32 v109, v31, v111
	global_store_dwordx2 v[168:169], v[32:33], off offset:3584 sc1
	v_cvt_pk_bf16_f32 v32, v34, v35
	v_cvt_pk_bf16_f32 v33, v108, v109
	v_mul_f32_e32 v100, v177, v100
	v_mul_f32_e32 v101, v177, v101
	v_mul_f32_e32 v102, v177, v102
	v_mul_f32_e32 v103, v177, v103
	v_mul_f32_e32 v104, v24, v104
	v_mul_f32_e32 v105, v25, v105
	v_mul_f32_e32 v106, v26, v106
	v_mul_f32_e32 v107, v27, v107
	global_store_dwordx2 v[166:167], v[32:33], off sc1
	v_cvt_pk_bf16_f32 v32, v104, v105
	v_cvt_pk_bf16_f32 v33, v106, v107
	v_fmamk_f32 v179, v179, 0x3a000000, v176
	v_mul_f32_e32 v96, v177, v96
	v_mul_f32_e32 v97, v177, v97
	v_mul_f32_e32 v98, v177, v98
	v_mul_f32_e32 v99, v177, v99
	v_mul_f32_e32 v100, v20, v100
	v_mul_f32_e32 v101, v21, v101
	v_mul_f32_e32 v102, v22, v102
	v_mul_f32_e32 v103, v23, v103
	global_store_dwordx2 v[166:167], v[32:33], off offset:512 sc1
	v_cvt_pk_bf16_f32 v32, v100, v101
	v_cvt_pk_bf16_f32 v33, v102, v103
	v_rsq_f32_e32 v140, v179
	v_mul_f32_e32 v92, v177, v92
	v_mul_f32_e32 v93, v177, v93
	v_mul_f32_e32 v94, v177, v94
	v_mul_f32_e32 v95, v177, v95
	v_mul_f32_e32 v96, v16, v96
	v_mul_f32_e32 v97, v17, v97
	v_mul_f32_e32 v98, v18, v98
	v_mul_f32_e32 v99, v19, v99
	global_store_dwordx2 v[166:167], v[32:33], off offset:1024 sc1
	v_cvt_pk_bf16_f32 v32, v96, v97
	v_cvt_pk_bf16_f32 v33, v98, v99
	v_mul_f32_e32 v88, v177, v88
	v_mul_f32_e32 v89, v177, v89
	v_mul_f32_e32 v90, v177, v90
	v_mul_f32_e32 v91, v177, v91
	v_mul_f32_e32 v92, v12, v92
	v_mul_f32_e32 v93, v13, v93
	v_mul_f32_e32 v94, v14, v94
	v_mul_f32_e32 v95, v15, v95
	global_store_dwordx2 v[166:167], v[32:33], off offset:1536 sc1
	v_cvt_pk_bf16_f32 v32, v92, v93
	v_cvt_pk_bf16_f32 v33, v94, v95
	v_mul_f32_e32 v84, v177, v84
	v_mul_f32_e32 v85, v177, v85
	v_mul_f32_e32 v86, v177, v86
	v_mul_f32_e32 v87, v177, v87
	v_mul_f32_e32 v88, v8, v88
	v_mul_f32_e32 v89, v9, v89
	v_mul_f32_e32 v90, v10, v90
	v_mul_f32_e32 v91, v11, v91
	global_store_dwordx2 v[166:167], v[32:33], off offset:2048 sc1
	v_cvt_pk_bf16_f32 v32, v88, v89
	v_cvt_pk_bf16_f32 v33, v90, v91
	v_mul_f32_e32 v80, v177, v80
	v_mul_f32_e32 v81, v177, v81
	v_mul_f32_e32 v82, v177, v82
	v_mul_f32_e32 v83, v177, v83
	v_mul_f32_e32 v84, v4, v84
	v_mul_f32_e32 v85, v5, v85
; __device__ __forceinline__ unsigned cvtpk2(float lo, float hi) { unsigned r; asm volatile("v_cvt_pk_bf16_f32 %0, %1, %2" : "=v"(r) : "v"(lo), "v"(hi)); return r; }
; __global__ void __launch_bounds__(NWAVES * 64, 2) hybrid_fwd(Args args) {
;     ...
;             for (int q = 0; q < 4; ++q) { const float rs = __builtin_amdgcn_rsqf(wave_sum(s[q]) * (1.f / DM) + NORM_EPS);
;                 v2u* o8 = (v2u*)(HB + (size_t)(m0 + q) * DM) + lane;
; #pragma unroll
;                 for (int j = 0; j < 8; ++j) { const f32x4 w = wmix[j]; v2u o; o.x = cvtpk2(v[q][j].x * rs * w.x, v[q][j].y * rs * w.y); o.y = cvtpk2(v[q][j].z * rs * w.z, v[q][j].w * rs * w.w); o8[64 * j] = o; } }
;         }
	v_mul_f32_e32 v86, v6, v86
	v_mul_f32_e32 v87, v7, v87
	global_store_dwordx2 v[166:167], v[32:33], off offset:2560 sc1
	v_cvt_pk_bf16_f32 v32, v84, v85
	v_cvt_pk_bf16_f32 v33, v86, v87
	v_mul_f32_e32 v80, v0, v80
	v_mul_f32_e32 v81, v1, v81
	v_mul_f32_e32 v82, v2, v82
	v_mul_f32_e32 v83, v3, v83
	v_mul_f32_e32 v76, v140, v76
	v_mul_f32_e32 v77, v140, v77
	v_mul_f32_e32 v78, v140, v78
	v_mul_f32_e32 v79, v140, v79
	global_store_dwordx2 v[166:167], v[32:33], off offset:3072 sc1
	v_cvt_pk_bf16_f32 v32, v80, v81
	v_cvt_pk_bf16_f32 v33, v82, v83
	v_mul_f32_e32 v72, v140, v72
	v_mul_f32_e32 v73, v140, v73
	v_mul_f32_e32 v74, v140, v74
	v_mul_f32_e32 v75, v140, v75
	v_mul_f32_e32 v76, v28, v76
	v_mul_f32_e32 v77, v29, v77
	v_mul_f32_e32 v78, v30, v78
	v_mul_f32_e32 v79, v31, v79
	global_store_dwordx2 v[166:167], v[32:33], off offset:3584 sc1
	v_cvt_pk_bf16_f32 v32, v76, v77
	v_cvt_pk_bf16_f32 v33, v78, v79
	v_mul_f32_e32 v68, v140, v68
	v_mul_f32_e32 v69, v140, v69
	v_mul_f32_e32 v70, v140, v70
	v_mul_f32_e32 v71, v140, v71
	v_mul_f32_e32 v72, v24, v72
	v_mul_f32_e32 v73, v25, v73
	v_mul_f32_e32 v74, v26, v74
	v_mul_f32_e32 v75, v27, v75
	global_store_dwordx2 v[164:165], v[32:33], off sc1
	v_cvt_pk_bf16_f32 v32, v72, v73
	v_cvt_pk_bf16_f32 v33, v74, v75
	v_mul_f32_e32 v60, v140, v60
	v_mul_f32_e32 v61, v140, v61
	v_mul_f32_e32 v62, v140, v62
	v_mul_f32_e32 v63, v140, v63
	v_mul_f32_e32 v68, v20, v68
	v_mul_f32_e32 v69, v21, v69
	v_mul_f32_e32 v70, v22, v70
	v_mul_f32_e32 v71, v23, v71
	global_store_dwordx2 v[164:165], v[32:33], off offset:512 sc1
	v_cvt_pk_bf16_f32 v32, v68, v69
	v_cvt_pk_bf16_f32 v33, v70, v71
	v_mul_f32_e32 v64, v140, v64
	v_mul_f32_e32 v65, v140, v65
	v_mul_f32_e32 v66, v140, v66
	v_mul_f32_e32 v67, v140, v67
	v_mul_f32_e32 v60, v16, v60
	v_mul_f32_e32 v61, v17, v61
	v_mul_f32_e32 v62, v18, v62
	v_mul_f32_e32 v63, v19, v63
	global_store_dwordx2 v[164:165], v[32:33], off offset:1024 sc1
	v_cvt_pk_bf16_f32 v32, v60, v61
	v_cvt_pk_bf16_f32 v33, v62, v63
	v_mul_f32_e32 v56, v140, v56
	v_mul_f32_e32 v57, v140, v57
	v_mul_f32_e32 v58, v140, v58
	v_mul_f32_e32 v59, v140, v59
	v_mul_f32_e32 v64, v12, v64
	v_mul_f32_e32 v65, v13, v65
	v_mul_f32_e32 v66, v14, v66
	v_mul_f32_e32 v67, v15, v67
	global_store_dwordx2 v[164:165], v[32:33], off offset:1536 sc1
	v_cvt_pk_bf16_f32 v32, v64, v65
	v_cvt_pk_bf16_f32 v33, v66, v67
	v_mul_f32_e32 v52, v140, v52
	v_mul_f32_e32 v53, v140, v53
	v_mul_f32_e32 v54, v140, v54
	v_mul_f32_e32 v55, v140, v55
	v_mul_f32_e32 v56, v8, v56
	v_mul_f32_e32 v57, v9, v57
	v_mul_f32_e32 v58, v10, v58
	v_mul_f32_e32 v59, v11, v59
	global_store_dwordx2 v[164:165], v[32:33], off offset:2048 sc1
	v_cvt_pk_bf16_f32 v32, v56, v57
	v_cvt_pk_bf16_f32 v33, v58, v59
	v_lshl_add_u64 v[162:163], v[162:163], 0, s[16:17]
	v_mul_f32_e32 v48, v140, v48
	v_mul_f32_e32 v49, v140, v49
	v_mul_f32_e32 v50, v140, v50
	v_mul_f32_e32 v51, v140, v51
	v_mul_f32_e32 v52, v4, v52
	v_mul_f32_e32 v53, v5, v53
	v_mul_f32_e32 v54, v6, v54
	v_mul_f32_e32 v55, v7, v55
	v_lshl_add_u64 v[160:161], v[160:161], 0, s[14:15]
	global_store_dwordx2 v[164:165], v[32:33], off offset:2560 sc1
	v_cvt_pk_bf16_f32 v32, v52, v53
	v_cvt_pk_bf16_f32 v33, v54, v55
	v_mul_f32_e32 v48, v0, v48
	v_mul_f32_e32 v49, v1, v49
	v_mul_f32_e32 v50, v2, v50
	v_mul_f32_e32 v51, v3, v51
	global_store_dwordx2 v[164:165], v[32:33], off offset:3072 sc1
	v_cvt_pk_bf16_f32 v32, v48, v49
	v_cvt_pk_bf16_f32 v33, v50, v51
	global_store_dwordx2 v[164:165], v[32:33], off offset:3584 sc1
	s_cbranch_scc1 .LBB0_25
